# phase-2 thin kv tile: 3 LDS stage buffers, k-stage loads issued two stages ahead (counted vmcnt(5))
# baseline (speedup 1.0000x reference)
; __device__ __forceinline__ int get_tid512() { int t = threadIdx.x; asm volatile("" : "+v"(t)); return t; }
; template <bool SWAP, class Epi, bool THIN = false> ...
;   const int tid = get_tid512(), lane = tid & 63, wid = tid >> 6, wr = wid >> 1, wc = wid & 1, fr = lane & 15, fq = lane >> 4;
;   const int NT = (N + 255) >> 8, MT = MTS >> 1, ntiles = MT * NT, ns = K >> 6;
;   const int full = MT >> 3;
;   int v = vid0;
;   if (v < voff) v += ((voff - v + grid - 1) / grid) * grid;
;   const int swz = (fr >> 1) & 7;
;   bool pre_issued = false;
;   for (; v < voff + ntiles; v += grid) {
;     const int w = v - voff;
;     int mt, nt;
;     if (w < full * 8 * NT) { const int sr = w / (8 * NT), rem = w - sr * 8 * NT; nt = rem >> 3; mt = sr * 8 + (rem & 7); }
;     else { const int w2 = w - full * 8 * NT, rl = MT - full * 8; nt = w2 / rl; mt = full * 8 + (w2 - nt * rl); }
;     unsigned ap[4], bp[4];
; #pragma unroll
;     for (int i = 0; i < 4; ++i) {
;       const int r = (tid >> 3) + 64 * i;
;       const int cs = tid & 7;
;       const int c = ((cs ^ ((r >> 1) & 7)) << 3);
;       const int sub = 2 * mt + (r >> 7);
;       const int g = sub / tpg, ti = sub - g * tpg;
;       int rig = ti * step - halo + (r & 127); rig = rig < 0 ? 0 : (rig > grows - 1 ? grows - 1 : rig);
;       ap[i] = (unsigned)((g * a_gstride + a_goff + rig) * lda + c);
;       int br = nt * 256 + r; br = br > N - 1 ? N - 1 : br;
;       bp[i] = (unsigned)(br * K + c);
;     }
.LBB0_1522:
	s_cmpk_gt_i32 s3, 0x14f
	s_cbranch_scc1 .LBB0_1673
	s_load_dwordx2 s[16:17], s[0:1], 0x1d0
	v_and_b32_e32 v4, 15, v2
	v_lshrrev_b32_e32 v7, 1, v2
	s_mov_b32 s4, 0x1ffffc0
	v_bfe_u32 v3, v2, 6, 1
	v_lshrrev_b32_e32 v5, 4, v2
	v_bfe_u32 v8, v2, 1, 3
	v_and_or_b32 v7, v7, s4, v4
	v_lshlrev_b32_e32 v4, 7, v4
	s_waitcnt lgkmcnt(0)
	s_add_u32 s18, s38, 0x80000
	v_bfe_u32 v6, v2, 4, 2
	v_ashrrev_i32_e32 v54, 3, v2
	v_xor_b32_e32 v9, v5, v2
	v_lshlrev_b32_e32 v56, 4, v2
	v_lshlrev_b32_e32 v7, 7, v7
	v_ashrrev_i32_e32 v57, 10, v2
	v_bitop3_b32 v2, v5, v8, 3 bitop3:0x6c
	v_lshl_or_b32 v4, v3, 14, v4
	s_addc_u32 s19, s39, 0
	v_lshlrev_b32_e32 v2, 4, v2
	v_bitop3_b32 v5, v6, v8, 4 bitop3:0x36
	v_or_b32_e32 v6, 0x18000, v4
	v_add_u32_e32 v8, 0x10000, v7
	v_lshlrev_b32_e32 v9, 3, v9
	v_add_u32_e32 v59, 64, v54
	v_add_u32_e32 v62, 0x80, v54
	v_add_u32_e32 v64, 0xc0, v54
	v_lshlrev_b32_e32 v5, 4, v5
	s_cmp_eq_u64 s[16:17], 0
	v_add_u32_e32 v82, v7, v2
	v_add_u32_e32 v83, v4, v2
	v_add_u32_e32 v86, v8, v2
	v_add_u32_e32 v87, v6, v2
	v_mbcnt_lo_u32_b32 v2, -1, 0
	v_and_b32_e32 v55, 56, v9
	v_cmp_eq_u32_e64 s[4:5], 0, v3
	v_and_b32_e32 v58, 0x7f, v54
	v_ashrrev_i32_e32 v60, 7, v59
	v_and_b32_e32 v61, 0x7f, v59
	v_ashrrev_i32_e32 v63, 7, v62
	v_ashrrev_i32_e32 v65, 7, v64
	v_and_b32_e32 v66, 0x7f, v64
	s_cselect_b64 s[20:21], -1, 0
	s_addk_i32 s3, 0xfef8
	s_mov_b32 s33, 0x38e38e39
	s_movk_i32 s74, 0xffee
	v_mov_b32_e32 v3, 0
	s_movk_i32 s75, 0x900
	v_add_u32_e32 v67, 0x8000, v56
	v_add_u32_e32 v68, 0x2000, v56
	v_add_u32_e32 v69, 0xa000, v56
	v_add_u32_e32 v70, 0x4000, v56
	v_add_u32_e32 v71, 0xc000, v56
	v_add_u32_e32 v72, 0x6000, v56
	v_add_u32_e32 v73, 0xe000, v56
	s_mov_b64 s[22:23], 0x80
	v_add_u32_e32 v74, 0x10000, v56
	v_add_u32_e32 v75, 0x18000, v56
	s_mov_b32 s76, 0x12000
	v_add_u32_e32 v76, 0x12000, v56
	v_add_u32_e32 v77, 0x1a000, v56
	v_add_u32_e32 v78, 0x14000, v56
	v_add_u32_e32 v79, 0x1c000, v56
	v_add_u32_e32 v80, 0x16000, v56
	v_add_u32_e32 v81, 0x1e000, v56
	v_add_u32_e32 v84, v7, v5
	v_add_u32_e32 v85, v4, v5
	s_mov_b64 s[24:25], 0x100
	v_add_u32_e32 v88, v8, v5
	v_add_u32_e32 v89, v6, v5
	v_add_u32_e32 v118, 0x1a000, v82
	v_add_u32_e32 v119, 0x1a000, v83
	v_add_u32_e32 v120, 0x1a000, v84
	v_add_u32_e32 v121, 0x1a000, v85
	s_mov_b64 s[26:27], 0x180
	s_mov_b64 s[28:29], 0x200
	s_mov_b64 s[38:39], 0x280
	s_mov_b64 s[40:41], 0x300
	s_mov_b64 s[42:43], 0x380
	s_mov_b64 s[44:45], 0x400
	s_mov_b64 s[48:49], 0x480
	s_movk_i32 s77, 0x240
	s_mov_b64 s[50:51], 0x500
	s_mov_b64 s[56:57], 0x580
	s_mov_b64 s[58:59], 0x600
	s_mov_b64 s[60:61], 0x680
	s_mov_b64 s[62:63], 0x700
	s_mov_b64 s[64:65], 0x780
	s_movk_i32 s78, 0xff
	s_mov_b32 s79, 0xc2fc0000
	s_movk_i32 s80, 0x2400
	v_mbcnt_hi_u32_b32 v90, -1, v2
	v_mov_b32_e32 v91, 0x42800000
	v_not_b32_e32 v92, 63
	s_branch .LBB0_1525

; template <bool SWAP, class Epi, bool THIN = false> ...
;     ...
;   for (; v < voff + ntiles; v += grid) {
;     const int w = v - voff;
;     int mt, nt;
;     if (w < full * 8 * NT) { const int sr = w / (8 * NT), rem = w - sr * 8 * NT; nt = rem >> 3; mt = sr * 8 + (rem & 7); }
;     else { const int w2 = w - full * 8 * NT, rl = MT - full * 8; nt = w2 / rl; mt = full * 8 + (w2 - nt * rl); }
;     unsigned ap[4], bp[4];
; #pragma unroll
;     for (int i = 0; i < 4; ++i) {
;       const int r = (tid >> 3) + 64 * i;
;       const int cs = tid & 7;
;       const int c = ((cs ^ ((r >> 1) & 7)) << 3);
;       const int sub = 2 * mt + (r >> 7);
;       const int g = sub / tpg, ti = sub - g * tpg;
;       int rig = ti * step - halo + (r & 127); rig = rig < 0 ? 0 : (rig > grows - 1 ? grows - 1 : rig);
;       ap[i] = (unsigned)((g * a_gstride + a_goff + rig) * lda + c);
;       int br = nt * 256 + r; br = br > N - 1 ? N - 1 : br;
;       bp[i] = (unsigned)(br * K + c);
;     }
;     const bool have_next = false;
;     f32x4 acc[4][8];
; #pragma unroll
;     for (int m = 0; m < 4; ++m)
; #pragma unroll
;       for (int n = 0; n < 8; ++n) acc[m][n] = (f32x4){0.f, 0.f, 0.f, 0.f};
;     if (!pre_issued) {
; #pragma unroll
;       for (int i = 0; i < 4; ++i) { GLDS16(A + (size_t)ap[i], smem + tid * 16 + i * 8192); GLDS16(Bt + (size_t)bp[i], smem + 32768 + tid * 16 + i * 8192); }
;     }
;     pre_issued = have_next;
;     for (int st = 0; st < ns; ++st) {
;       asm volatile("s_waitcnt vmcnt(0)" ::: "memory");
;       __builtin_amdgcn_s_barrier();
;       asm volatile("" ::: "memory");
;       if (st + 1 < ns) {
;         char* nb = smem + ((st + 1) & 1) * 65536;
;         const int ko = (st + 1) * 64;
; #pragma unroll
;         for (int i = 0; i < 4; ++i) { GLDS16(A + (size_t)(ap[i] + ko), nb + tid * 16 + i * 8192); GLDS16(Bt + (size_t)(bp[i] + ko), nb + 32768 + tid * 16 + i * 8192); }
;       }
;       const char* sa = smem + (st & 1) * 65536 + (wr * 64 + fr) * 128;
;       const char* sb = smem + (st & 1) * 65536 + 32768 + (wc * 128 + fr) * 128;
;       if constexpr (THIN) {
;         if (wc == 0) {
; #pragma unroll
;           for (int ks = 0; ks < 2; ++ks) {
;             bf16x8 af[4], bf[2];
; #pragma unroll
;             for (int m = 0; m < 4; ++m) af[m] = *(const bf16x8*)(sa + m * 2048 + (((ks * 4 + fq) ^ swz) << 4));
; #pragma unroll
.LBB0_1525:
	s_ashr_i32 s7, s3, 31
	s_lshr_b32 s7, s7, 29
	s_add_i32 s6, s3, 0x108
	s_add_i32 s7, s3, s7
	s_and_b32 s7, s7, -8
	s_and_b32 s6, s6, 7
	s_or_b32 s6, s7, s6
	s_lshl_b32 s9, s6, 1
	v_add_u32_e32 v2, s9, v57
	v_mul_hi_i32 v4, v2, s33
	v_lshrrev_b32_e32 v5, 31, v4
	v_ashrrev_i32_e32 v4, 2, v4
	v_add_u32_e32 v6, v4, v5
	s_sub_i32 s8, s3, s7
	v_mad_u64_u32 v[4:5], s[6:7], v6, s74, v[2:3]
	v_lshl_or_b32 v2, v4, 7, v58
	v_min_i32_e32 v2, 0x8ff, v2
	v_cmp_lt_i32_e32 vcc, -1, v4
	s_ashr_i32 s46, s8, 3
	s_lshl_b32 s8, s46, 8
	v_cndmask_b32_e32 v2, 0, v2, vcc
	v_mad_u64_u32 v[4:5], s[6:7], v6, s75, v[2:3]
	v_lshl_or_b32 v2, v4, 10, v55
	v_add_u32_e32 v4, s8, v54
	v_min_i32_e32 v4, 31, v4
	v_lshl_or_b32 v38, v4, 10, v55
	v_add_u32_e32 v4, s9, v60
	v_mul_hi_i32 v5, v4, s33
	v_lshrrev_b32_e32 v6, 31, v5
	v_ashrrev_i32_e32 v5, 2, v5
	v_add_u32_e32 v6, v5, v6
	v_mad_u64_u32 v[4:5], s[6:7], v6, s74, v[4:5]
	v_lshl_or_b32 v5, v4, 7, v61
	v_min_i32_e32 v5, 0x8ff, v5
	v_cmp_lt_i32_e32 vcc, -1, v4
	v_add_u32_e32 v8, s9, v65
	v_lshl_add_u64 v[46:47], v[2:3], 1, s[36:37]
	v_cndmask_b32_e32 v4, 0, v5, vcc
	v_mad_u64_u32 v[4:5], s[6:7], v6, s75, v[4:5]
	v_add_u32_e32 v5, s8, v59
	v_min_i32_e32 v5, 31, v5
	v_add_u32_e32 v6, s9, v63
	v_lshl_or_b32 v40, v5, 10, v55
	v_mul_hi_i32 v5, v6, s33
	v_lshrrev_b32_e32 v7, 31, v5
	v_ashrrev_i32_e32 v5, 2, v5
	v_add_u32_e32 v5, v5, v7
	v_mad_u64_u32 v[6:7], s[6:7], v5, s74, v[6:7]
	v_lshl_or_b32 v7, v6, 7, v58
	v_min_i32_e32 v7, 0x8ff, v7
	v_cmp_lt_i32_e32 vcc, -1, v6
	v_mov_b32_e32 v39, v3
	v_lshl_or_b32 v4, v4, 10, v55
	v_cndmask_b32_e32 v6, 0, v7, vcc
	v_mad_u64_u32 v[6:7], s[6:7], v5, s75, v[6:7]
	v_add_u32_e32 v5, s8, v62
	v_min_i32_e32 v5, 31, v5
	v_lshl_or_b32 v42, v5, 10, v55
	v_mul_hi_i32 v5, v8, s33
	v_lshrrev_b32_e32 v7, 31, v5
	v_ashrrev_i32_e32 v5, 2, v5
	v_add_u32_e32 v5, v5, v7
	v_mad_u64_u32 v[8:9], s[6:7], v5, s74, v[8:9]
	v_lshl_or_b32 v7, v8, 7, v66
	v_min_i32_e32 v7, 0x8ff, v7
	v_cmp_lt_i32_e32 vcc, -1, v8
	v_lshl_add_u64 v[10:11], v[38:39], 1, s[18:19]
	v_mov_b32_e32 v41, v3
	v_cndmask_b32_e32 v8, 0, v7, vcc
	v_mad_u64_u32 v[8:9], s[6:7], v5, s75, v[8:9]
	v_add_u32_e32 v5, s8, v64
	v_readfirstlane_b32 s6, v56
	v_min_i32_e32 v5, 31, v5
	s_mov_b32 m0, s6
	v_readfirstlane_b32 s6, v67
	v_lshl_or_b32 v44, v5, 10, v55
	global_load_lds_dwordx4 v[46:47], off
	s_mov_b32 m0, s6
	v_mov_b32_e32 v5, v3
	v_readfirstlane_b32 s6, v68
	global_load_lds_dwordx4 v[10:11], off
	v_lshl_add_u64 v[48:49], v[4:5], 1, s[36:37]
	s_mov_b32 m0, s6
	v_readfirstlane_b32 s6, v69
	v_lshl_or_b32 v6, v6, 10, v55
	global_load_lds_dwordx4 v[48:49], off
	v_lshl_add_u64 v[4:5], v[40:41], 1, s[18:19]
	s_mov_b32 m0, s6
	v_mov_b32_e32 v7, v3
	v_readfirstlane_b32 s6, v70
	v_lshl_add_u64 v[50:51], v[6:7], 1, s[36:37]
	s_mov_b32 m0, s6
	v_mov_b32_e32 v43, v3
	v_readfirstlane_b32 s6, v71
	v_lshl_or_b32 v8, v8, 10, v55
	global_load_lds_dwordx4 v[50:51], off
	v_lshl_add_u64 v[4:5], v[42:43], 1, s[18:19]
	s_mov_b32 m0, s6
	v_mov_b32_e32 v9, v3
	v_readfirstlane_b32 s6, v72
	v_lshl_add_u64 v[52:53], v[8:9], 1, s[36:37]
	s_mov_b32 m0, s6
	v_mov_b32_e32 v45, v3
	v_readfirstlane_b32 s6, v73
	global_load_lds_dwordx4 v[52:53], off
	v_lshl_add_u64 v[4:5], v[44:45], 1, s[18:19]
	s_mov_b32 m0, s6
	v_readfirstlane_b32 s6, v74
	v_readfirstlane_b32 s6, v56
	s_add_i32 m0, s6, 0x10000
	v_lshl_add_u64 v[4:5], v[46:47], 0, s[22:23]
	global_load_lds_dwordx4 v[4:5], off
	v_or_b32_e32 v2, 64, v38
	s_add_i32 m0, s6, 0x18000
	v_lshl_add_u64 v[4:5], v[2:3], 1, s[18:19]
	global_load_lds_dwordx4 v[4:5], off
	s_add_i32 m0, s6, 0x12000
	v_lshl_add_u64 v[4:5], v[48:49], 0, s[22:23]
	global_load_lds_dwordx4 v[4:5], off
	s_add_i32 m0, s6, 0x14000
	v_lshl_add_u64 v[4:5], v[50:51], 0, s[22:23]
	global_load_lds_dwordx4 v[4:5], off
	s_add_i32 m0, s6, 0x16000
	v_lshl_add_u64 v[4:5], v[52:53], 0, s[22:23]
	global_load_lds_dwordx4 v[4:5], off
	s_waitcnt vmcnt(5)
	s_barrier
	v_readfirstlane_b32 s6, v56
	s_add_i32 m0, s6, 0x1a000
	v_lshl_add_u64 v[4:5], v[46:47], 0, s[24:25]
	global_load_lds_dwordx4 v[4:5], off
	v_or_b32_e32 v2, 0x80, v38
	s_add_i32 m0, s6, 0x22000
	v_lshl_add_u64 v[4:5], v[2:3], 1, s[18:19]
	global_load_lds_dwordx4 v[4:5], off
	s_add_i32 m0, s6, 0x1c000
	v_lshl_add_u64 v[4:5], v[48:49], 0, s[24:25]
	global_load_lds_dwordx4 v[4:5], off
	s_add_i32 m0, s6, 0x1e000
	v_lshl_add_u64 v[4:5], v[50:51], 0, s[24:25]
	global_load_lds_dwordx4 v[4:5], off
	s_add_i32 m0, s6, 0x20000
	v_lshl_add_u64 v[4:5], v[52:53], 0, s[24:25]
	global_load_lds_dwordx4 v[4:5], off
	v_mov_b32_e32 v2, v3
	v_mov_b32_e32 v4, v3
	v_mov_b32_e32 v5, v3
	v_mov_b64_e32 v[28:29], v[4:5]
	v_mov_b64_e32 v[24:25], v[4:5]
	v_mov_b64_e32 v[20:21], v[4:5]
	v_mov_b64_e32 v[16:17], v[4:5]
	v_mov_b64_e32 v[12:13], v[4:5]
	v_mov_b64_e32 v[8:9], v[4:5]
	v_mov_b64_e32 v[32:33], v[4:5]
	v_mov_b64_e32 v[36:37], v[4:5]
	v_mov_b64_e32 v[26:27], v[2:3]
	v_mov_b64_e32 v[22:23], v[2:3]
	v_mov_b64_e32 v[18:19], v[2:3]
	v_mov_b64_e32 v[14:15], v[2:3]
	v_mov_b64_e32 v[10:11], v[2:3]
	v_mov_b64_e32 v[6:7], v[2:3]
	v_mov_b64_e32 v[30:31], v[2:3]
	v_mov_b64_e32 v[34:35], v[2:3]
	s_and_saveexec_b64 s[6:7], s[4:5]
	s_cbranch_execz .LBB0_1527
	ds_read_b128 v[4:7], v83 offset:32768
	ds_read_b128 v[8:11], v83 offset:34816
	ds_read_b128 v[12:15], v82
	ds_read_b128 v[16:19], v82 offset:2048
	ds_read_b128 v[28:31], v82 offset:4096
	ds_read_b128 v[32:35], v82 offset:6144
	ds_read_b128 v[102:105], v85 offset:32768
	s_waitcnt lgkmcnt(0)
	v_mfma_f32_16x16x32_bf16 v[20:23], v[4:7], v[12:15], 0
	v_mfma_f32_16x16x32_bf16 v[12:15], v[8:11], v[12:15], 0
	v_mfma_f32_16x16x32_bf16 v[24:27], v[4:7], v[16:19], 0
	v_mfma_f32_16x16x32_bf16 v[16:19], v[8:11], v[16:19], 0
	v_mfma_f32_16x16x32_bf16 v[98:101], v[8:11], v[28:31], 0
	v_mfma_f32_16x16x32_bf16 v[106:109], v[8:11], v[32:35], 0
	ds_read_b128 v[110:113], v85 offset:34816
	ds_read_b128 v[8:11], v84
	ds_read_b128 v[114:117], v84 offset:2048
	v_mfma_f32_16x16x32_bf16 v[94:97], v[4:7], v[28:31], 0
	v_mfma_f32_16x16x32_bf16 v[4:7], v[4:7], v[32:35], 0
	s_waitcnt lgkmcnt(0)
	v_mfma_f32_16x16x32_bf16 v[34:37], v[102:105], v[8:11], v[20:23]
	v_mfma_f32_16x16x32_bf16 v[30:33], v[110:113], v[8:11], v[12:15]
	v_mfma_f32_16x16x32_bf16 v[26:29], v[102:105], v[114:117], v[24:27]
	v_mfma_f32_16x16x32_bf16 v[22:25], v[110:113], v[114:117], v[16:19]
	ds_read_b128 v[8:11], v84 offset:4096
	ds_read_b128 v[114:117], v84 offset:6144
	s_waitcnt lgkmcnt(0)
	v_mfma_f32_16x16x32_bf16 v[18:21], v[102:105], v[8:11], v[94:97]
	v_mfma_f32_16x16x32_bf16 v[14:17], v[110:113], v[8:11], v[98:101]
	v_mfma_f32_16x16x32_bf16 v[10:13], v[102:105], v[114:117], v[4:7]
	v_mfma_f32_16x16x32_bf16 v[6:9], v[110:113], v[114:117], v[106:109]
; #define GLDS16(gp, lp) __builtin_amdgcn_global_load_lds((const unsigned*)(gp), (__attribute__((address_space(3))) unsigned*)(lp), 16, 0, 0)
; template <bool SWAP, class Epi, bool THIN = false> ...
;     ...
;     for (int st = 0; st < ns; ++st) {
;       asm volatile("s_waitcnt vmcnt(0)" ::: "memory");
;       __builtin_amdgcn_s_barrier();
;       asm volatile("" ::: "memory");
;       if (st + 1 < ns) {
;         char* nb = smem + ((st + 1) & 1) * 65536;
;         const int ko = (st + 1) * 64;
; #pragma unroll
;         for (int i = 0; i < 4; ++i) { GLDS16(A + (size_t)(ap[i] + ko), nb + tid * 16 + i * 8192); GLDS16(Bt + (size_t)(bp[i] + ko), nb + 32768 + tid * 16 + i * 8192); }
;       }
;       const char* sa = smem + (st & 1) * 65536 + (wr * 64 + fr) * 128;
;       const char* sb = smem + (st & 1) * 65536 + 32768 + (wc * 128 + fr) * 128;
;       if constexpr (THIN) {
;         if (wc == 0) {
; #pragma unroll
;           for (int ks = 0; ks < 2; ++ks) {
;             bf16x8 af[4], bf[2];
; #pragma unroll
;             for (int m = 0; m < 4; ++m) af[m] = *(const bf16x8*)(sa + m * 2048 + (((ks * 4 + fq) ^ swz) << 4));
; #pragma unroll
;             for (int n = 0; n < 2; ++n) bf[n] = *(const bf16x8*)(sb + n * 2048 + (((ks * 4 + fq) ^ swz) << 4));
; #pragma unroll
;             for (int m = 0; m < 4; ++m)
; #pragma unroll
;               for (int n = 0; n < 2; ++n)
;                 acc[m][n] = SWAP ? __builtin_amdgcn_mfma_f32_16x16x32_bf16(bf[n], af[m], acc[m][n], 0, 0, 0)
;                                  : __builtin_amdgcn_mfma_f32_16x16x32_bf16(af[m], bf[n], acc[m][n], 0, 0, 0);
;           }
.LBB0_1527:
	s_or_b64 exec, exec, s[6:7]
	s_waitcnt vmcnt(5)
	s_barrier
	v_readfirstlane_b32 s6, v56
	s_add_i32 m0, s6, 0x0
	v_lshl_add_u64 v[4:5], v[46:47], 0, s[26:27]
	global_load_lds_dwordx4 v[4:5], off
	v_or_b32_e32 v2, 0xc0, v38
	s_add_i32 m0, s6, 0x8000
	v_lshl_add_u64 v[4:5], v[2:3], 1, s[18:19]
	global_load_lds_dwordx4 v[4:5], off
	s_add_i32 m0, s6, 0x2000
	v_lshl_add_u64 v[4:5], v[48:49], 0, s[26:27]
	global_load_lds_dwordx4 v[4:5], off
	s_add_i32 m0, s6, 0x4000
	v_lshl_add_u64 v[4:5], v[50:51], 0, s[26:27]
	global_load_lds_dwordx4 v[4:5], off
	s_add_i32 m0, s6, 0x6000
	v_lshl_add_u64 v[4:5], v[52:53], 0, s[26:27]
	global_load_lds_dwordx4 v[4:5], off
	s_and_saveexec_b64 s[6:7], s[4:5]
	s_cbranch_execz .LBB0_1529
	ds_read_b128 v[94:97], v87
	ds_read_b128 v[98:101], v87 offset:2048
	ds_read_b128 v[102:105], v86
	ds_read_b128 v[106:109], v86 offset:2048
	s_waitcnt lgkmcnt(0)
	v_mfma_f32_16x16x32_bf16 v[34:37], v[94:97], v[102:105], v[34:37]
	v_mfma_f32_16x16x32_bf16 v[30:33], v[98:101], v[102:105], v[30:33]
	v_mfma_f32_16x16x32_bf16 v[26:29], v[94:97], v[106:109], v[26:29]
	v_mfma_f32_16x16x32_bf16 v[22:25], v[98:101], v[106:109], v[22:25]
	ds_read_b128 v[102:105], v86 offset:4096
	ds_read_b128 v[106:109], v86 offset:6144
	s_waitcnt lgkmcnt(0)
	v_mfma_f32_16x16x32_bf16 v[18:21], v[94:97], v[102:105], v[18:21]
	v_mfma_f32_16x16x32_bf16 v[10:13], v[94:97], v[106:109], v[10:13]
	ds_read_b128 v[94:97], v89
	v_mfma_f32_16x16x32_bf16 v[14:17], v[98:101], v[102:105], v[14:17]
	v_mfma_f32_16x16x32_bf16 v[4:7], v[98:101], v[106:109], v[6:9]
	ds_read_b128 v[98:101], v89 offset:2048
	ds_read_b128 v[102:105], v88
	ds_read_b128 v[106:109], v88 offset:2048
	s_waitcnt lgkmcnt(0)
	v_mfma_f32_16x16x32_bf16 v[34:37], v[94:97], v[102:105], v[34:37]
	v_mfma_f32_16x16x32_bf16 v[30:33], v[98:101], v[102:105], v[30:33]
	v_mfma_f32_16x16x32_bf16 v[26:29], v[94:97], v[106:109], v[26:29]
	v_mfma_f32_16x16x32_bf16 v[22:25], v[98:101], v[106:109], v[22:25]
	ds_read_b128 v[102:105], v88 offset:4096
	ds_read_b128 v[106:109], v88 offset:6144
	s_waitcnt lgkmcnt(0)
	v_mfma_f32_16x16x32_bf16 v[18:21], v[94:97], v[102:105], v[18:21]
	v_mfma_f32_16x16x32_bf16 v[14:17], v[98:101], v[102:105], v[14:17]
	v_mfma_f32_16x16x32_bf16 v[10:13], v[94:97], v[106:109], v[10:13]
	v_mfma_f32_16x16x32_bf16 v[6:9], v[98:101], v[106:109], v[4:7]
.LBB0_1529:
	s_or_b64 exec, exec, s[6:7]
	s_waitcnt vmcnt(5)
	s_barrier
	v_readfirstlane_b32 s6, v56
	s_add_i32 m0, s6, 0x10000
	v_lshl_add_u64 v[4:5], v[46:47], 0, s[28:29]
	global_load_lds_dwordx4 v[4:5], off
	v_or_b32_e32 v2, 0x100, v38
	s_add_i32 m0, s6, 0x18000
	v_lshl_add_u64 v[4:5], v[2:3], 1, s[18:19]
	global_load_lds_dwordx4 v[4:5], off
	s_add_i32 m0, s6, 0x12000
	v_lshl_add_u64 v[4:5], v[48:49], 0, s[28:29]
	global_load_lds_dwordx4 v[4:5], off
	s_add_i32 m0, s6, 0x14000
	v_lshl_add_u64 v[4:5], v[50:51], 0, s[28:29]
	global_load_lds_dwordx4 v[4:5], off
	s_add_i32 m0, s6, 0x16000
	v_lshl_add_u64 v[4:5], v[52:53], 0, s[28:29]
	global_load_lds_dwordx4 v[4:5], off
	s_and_saveexec_b64 s[6:7], s[4:5]
	s_cbranch_execz .LBB0_1531
	ds_read_b128 v[94:97], v119 offset:32768
	ds_read_b128 v[98:101], v119 offset:34816
	ds_read_b128 v[102:105], v118
	ds_read_b128 v[106:109], v118 offset:2048
	s_waitcnt lgkmcnt(0)
	v_mfma_f32_16x16x32_bf16 v[34:37], v[94:97], v[102:105], v[34:37]
	v_mfma_f32_16x16x32_bf16 v[30:33], v[98:101], v[102:105], v[30:33]
	v_mfma_f32_16x16x32_bf16 v[26:29], v[94:97], v[106:109], v[26:29]
	v_mfma_f32_16x16x32_bf16 v[22:25], v[98:101], v[106:109], v[22:25]
	ds_read_b128 v[102:105], v118 offset:4096
	ds_read_b128 v[106:109], v118 offset:6144
	s_waitcnt lgkmcnt(0)
	v_mfma_f32_16x16x32_bf16 v[18:21], v[94:97], v[102:105], v[18:21]
	v_mfma_f32_16x16x32_bf16 v[10:13], v[94:97], v[106:109], v[10:13]
	ds_read_b128 v[94:97], v121 offset:32768
	v_mfma_f32_16x16x32_bf16 v[14:17], v[98:101], v[102:105], v[14:17]
	v_mfma_f32_16x16x32_bf16 v[4:7], v[98:101], v[106:109], v[6:9]
	ds_read_b128 v[98:101], v121 offset:34816
	ds_read_b128 v[102:105], v120
	ds_read_b128 v[106:109], v120 offset:2048
	s_waitcnt lgkmcnt(0)
	v_mfma_f32_16x16x32_bf16 v[34:37], v[94:97], v[102:105], v[34:37]
	v_mfma_f32_16x16x32_bf16 v[30:33], v[98:101], v[102:105], v[30:33]
	v_mfma_f32_16x16x32_bf16 v[26:29], v[94:97], v[106:109], v[26:29]
	v_mfma_f32_16x16x32_bf16 v[22:25], v[98:101], v[106:109], v[22:25]
	ds_read_b128 v[102:105], v120 offset:4096
	ds_read_b128 v[106:109], v120 offset:6144
	s_waitcnt lgkmcnt(0)
	v_mfma_f32_16x16x32_bf16 v[18:21], v[94:97], v[102:105], v[18:21]
	v_mfma_f32_16x16x32_bf16 v[14:17], v[98:101], v[102:105], v[14:17]
	v_mfma_f32_16x16x32_bf16 v[10:13], v[94:97], v[106:109], v[10:13]
	v_mfma_f32_16x16x32_bf16 v[6:9], v[98:101], v[106:109], v[4:7]
; #define GLDS16(gp, lp) __builtin_amdgcn_global_load_lds((const unsigned*)(gp), (__attribute__((address_space(3))) unsigned*)(lp), 16, 0, 0)
; template <bool SWAP, class Epi, bool THIN = false> ...
;     ...
;     for (int st = 0; st < ns; ++st) {
;       asm volatile("s_waitcnt vmcnt(0)" ::: "memory");
;       __builtin_amdgcn_s_barrier();
;       asm volatile("" ::: "memory");
;       if (st + 1 < ns) {
;         char* nb = smem + ((st + 1) & 1) * 65536;
;         const int ko = (st + 1) * 64;
; #pragma unroll
;         for (int i = 0; i < 4; ++i) { GLDS16(A + (size_t)(ap[i] + ko), nb + tid * 16 + i * 8192); GLDS16(Bt + (size_t)(bp[i] + ko), nb + 32768 + tid * 16 + i * 8192); }
;       }
;       const char* sa = smem + (st & 1) * 65536 + (wr * 64 + fr) * 128;
;       const char* sb = smem + (st & 1) * 65536 + 32768 + (wc * 128 + fr) * 128;
;       if constexpr (THIN) {
;         if (wc == 0) {
; #pragma unroll
;           for (int ks = 0; ks < 2; ++ks) {
;             bf16x8 af[4], bf[2];
; #pragma unroll
;             for (int m = 0; m < 4; ++m) af[m] = *(const bf16x8*)(sa + m * 2048 + (((ks * 4 + fq) ^ swz) << 4));
; #pragma unroll
;             for (int n = 0; n < 2; ++n) bf[n] = *(const bf16x8*)(sb + n * 2048 + (((ks * 4 + fq) ^ swz) << 4));
; #pragma unroll
;             for (int m = 0; m < 4; ++m)
; #pragma unroll
;               for (int n = 0; n < 2; ++n)
;                 acc[m][n] = SWAP ? __builtin_amdgcn_mfma_f32_16x16x32_bf16(bf[n], af[m], acc[m][n], 0, 0, 0)
;                                  : __builtin_amdgcn_mfma_f32_16x16x32_bf16(af[m], bf[n], acc[m][n], 0, 0, 0);
;           }
.LBB0_1531:
	s_or_b64 exec, exec, s[6:7]
	s_waitcnt vmcnt(5)
	s_barrier
	v_readfirstlane_b32 s6, v56
	s_add_i32 m0, s6, 0x1a000
	v_lshl_add_u64 v[4:5], v[46:47], 0, s[38:39]
	global_load_lds_dwordx4 v[4:5], off
	v_or_b32_e32 v2, 0x140, v38
	s_add_i32 m0, s6, 0x22000
	v_lshl_add_u64 v[4:5], v[2:3], 1, s[18:19]
	global_load_lds_dwordx4 v[4:5], off
	s_add_i32 m0, s6, 0x1c000
	v_lshl_add_u64 v[4:5], v[48:49], 0, s[38:39]
	global_load_lds_dwordx4 v[4:5], off
	s_add_i32 m0, s6, 0x1e000
	v_lshl_add_u64 v[4:5], v[50:51], 0, s[38:39]
	global_load_lds_dwordx4 v[4:5], off
	s_add_i32 m0, s6, 0x20000
	v_lshl_add_u64 v[4:5], v[52:53], 0, s[38:39]
	global_load_lds_dwordx4 v[4:5], off
	s_and_saveexec_b64 s[6:7], s[4:5]
	s_cbranch_execz .LBB0_1533
	ds_read_b128 v[94:97], v83 offset:32768
	ds_read_b128 v[98:101], v83 offset:34816
	ds_read_b128 v[102:105], v82
	ds_read_b128 v[106:109], v82 offset:2048
	s_waitcnt lgkmcnt(0)
	v_mfma_f32_16x16x32_bf16 v[34:37], v[94:97], v[102:105], v[34:37]
	v_mfma_f32_16x16x32_bf16 v[30:33], v[98:101], v[102:105], v[30:33]
	v_mfma_f32_16x16x32_bf16 v[26:29], v[94:97], v[106:109], v[26:29]
	v_mfma_f32_16x16x32_bf16 v[22:25], v[98:101], v[106:109], v[22:25]
	ds_read_b128 v[102:105], v82 offset:4096
	ds_read_b128 v[106:109], v82 offset:6144
	s_waitcnt lgkmcnt(0)
	v_mfma_f32_16x16x32_bf16 v[18:21], v[94:97], v[102:105], v[18:21]
	v_mfma_f32_16x16x32_bf16 v[10:13], v[94:97], v[106:109], v[10:13]
	ds_read_b128 v[94:97], v85 offset:32768
	v_mfma_f32_16x16x32_bf16 v[14:17], v[98:101], v[102:105], v[14:17]
	v_mfma_f32_16x16x32_bf16 v[4:7], v[98:101], v[106:109], v[6:9]
	ds_read_b128 v[98:101], v85 offset:34816
	ds_read_b128 v[102:105], v84
	ds_read_b128 v[106:109], v84 offset:2048
	s_waitcnt lgkmcnt(0)
	v_mfma_f32_16x16x32_bf16 v[34:37], v[94:97], v[102:105], v[34:37]
	v_mfma_f32_16x16x32_bf16 v[30:33], v[98:101], v[102:105], v[30:33]
	v_mfma_f32_16x16x32_bf16 v[26:29], v[94:97], v[106:109], v[26:29]
	v_mfma_f32_16x16x32_bf16 v[22:25], v[98:101], v[106:109], v[22:25]
	ds_read_b128 v[102:105], v84 offset:4096
	ds_read_b128 v[106:109], v84 offset:6144
	s_waitcnt lgkmcnt(0)
	v_mfma_f32_16x16x32_bf16 v[18:21], v[94:97], v[102:105], v[18:21]
	v_mfma_f32_16x16x32_bf16 v[14:17], v[98:101], v[102:105], v[14:17]
	v_mfma_f32_16x16x32_bf16 v[10:13], v[94:97], v[106:109], v[10:13]
	v_mfma_f32_16x16x32_bf16 v[6:9], v[98:101], v[106:109], v[4:7]
.LBB0_1533:
	s_or_b64 exec, exec, s[6:7]
	s_waitcnt vmcnt(5)
	s_barrier
	v_readfirstlane_b32 s6, v56
	s_add_i32 m0, s6, 0x0
	v_lshl_add_u64 v[4:5], v[46:47], 0, s[40:41]
	global_load_lds_dwordx4 v[4:5], off
	v_or_b32_e32 v2, 0x180, v38
	s_add_i32 m0, s6, 0x8000
	v_lshl_add_u64 v[4:5], v[2:3], 1, s[18:19]
	global_load_lds_dwordx4 v[4:5], off
	s_add_i32 m0, s6, 0x2000
	v_lshl_add_u64 v[4:5], v[48:49], 0, s[40:41]
	global_load_lds_dwordx4 v[4:5], off
	s_add_i32 m0, s6, 0x4000
	v_lshl_add_u64 v[4:5], v[50:51], 0, s[40:41]
	global_load_lds_dwordx4 v[4:5], off
	s_add_i32 m0, s6, 0x6000
	v_lshl_add_u64 v[4:5], v[52:53], 0, s[40:41]
	global_load_lds_dwordx4 v[4:5], off
	s_and_saveexec_b64 s[6:7], s[4:5]
	s_cbranch_execz .LBB0_1535
	ds_read_b128 v[94:97], v87
	ds_read_b128 v[98:101], v87 offset:2048
	ds_read_b128 v[102:105], v86
	ds_read_b128 v[106:109], v86 offset:2048
	s_waitcnt lgkmcnt(0)
	v_mfma_f32_16x16x32_bf16 v[34:37], v[94:97], v[102:105], v[34:37]
	v_mfma_f32_16x16x32_bf16 v[30:33], v[98:101], v[102:105], v[30:33]
	v_mfma_f32_16x16x32_bf16 v[26:29], v[94:97], v[106:109], v[26:29]
	v_mfma_f32_16x16x32_bf16 v[22:25], v[98:101], v[106:109], v[22:25]
	ds_read_b128 v[102:105], v86 offset:4096
	ds_read_b128 v[106:109], v86 offset:6144
	s_waitcnt lgkmcnt(0)
	v_mfma_f32_16x16x32_bf16 v[18:21], v[94:97], v[102:105], v[18:21]
	v_mfma_f32_16x16x32_bf16 v[10:13], v[94:97], v[106:109], v[10:13]
	ds_read_b128 v[94:97], v89
	v_mfma_f32_16x16x32_bf16 v[14:17], v[98:101], v[102:105], v[14:17]
	v_mfma_f32_16x16x32_bf16 v[4:7], v[98:101], v[106:109], v[6:9]
	ds_read_b128 v[98:101], v89 offset:2048
	ds_read_b128 v[102:105], v88
	ds_read_b128 v[106:109], v88 offset:2048
	s_waitcnt lgkmcnt(0)
	v_mfma_f32_16x16x32_bf16 v[34:37], v[94:97], v[102:105], v[34:37]
	v_mfma_f32_16x16x32_bf16 v[30:33], v[98:101], v[102:105], v[30:33]
	v_mfma_f32_16x16x32_bf16 v[26:29], v[94:97], v[106:109], v[26:29]
	v_mfma_f32_16x16x32_bf16 v[22:25], v[98:101], v[106:109], v[22:25]
	ds_read_b128 v[102:105], v88 offset:4096
	ds_read_b128 v[106:109], v88 offset:6144
	s_waitcnt lgkmcnt(0)
	v_mfma_f32_16x16x32_bf16 v[18:21], v[94:97], v[102:105], v[18:21]
	v_mfma_f32_16x16x32_bf16 v[14:17], v[98:101], v[102:105], v[14:17]
	v_mfma_f32_16x16x32_bf16 v[10:13], v[94:97], v[106:109], v[10:13]
	v_mfma_f32_16x16x32_bf16 v[6:9], v[98:101], v[106:109], v[4:7]
; #define GLDS16(gp, lp) __builtin_amdgcn_global_load_lds((const unsigned*)(gp), (__attribute__((address_space(3))) unsigned*)(lp), 16, 0, 0)
; template <bool SWAP, class Epi, bool THIN = false> ...
;     ...
;     for (int st = 0; st < ns; ++st) {
;       asm volatile("s_waitcnt vmcnt(0)" ::: "memory");
;       __builtin_amdgcn_s_barrier();
;       asm volatile("" ::: "memory");
;       if (st + 1 < ns) {
;         char* nb = smem + ((st + 1) & 1) * 65536;
;         const int ko = (st + 1) * 64;
; #pragma unroll
;         for (int i = 0; i < 4; ++i) { GLDS16(A + (size_t)(ap[i] + ko), nb + tid * 16 + i * 8192); GLDS16(Bt + (size_t)(bp[i] + ko), nb + 32768 + tid * 16 + i * 8192); }
;       }
;       const char* sa = smem + (st & 1) * 65536 + (wr * 64 + fr) * 128;
;       const char* sb = smem + (st & 1) * 65536 + 32768 + (wc * 128 + fr) * 128;
;       if constexpr (THIN) {
;         if (wc == 0) {
; #pragma unroll
;           for (int ks = 0; ks < 2; ++ks) {
;             bf16x8 af[4], bf[2];
; #pragma unroll
;             for (int m = 0; m < 4; ++m) af[m] = *(const bf16x8*)(sa + m * 2048 + (((ks * 4 + fq) ^ swz) << 4));
; #pragma unroll
;             for (int n = 0; n < 2; ++n) bf[n] = *(const bf16x8*)(sb + n * 2048 + (((ks * 4 + fq) ^ swz) << 4));
; #pragma unroll
;             for (int m = 0; m < 4; ++m)
; #pragma unroll
;               for (int n = 0; n < 2; ++n)
;                 acc[m][n] = SWAP ? __builtin_amdgcn_mfma_f32_16x16x32_bf16(bf[n], af[m], acc[m][n], 0, 0, 0)
;                                  : __builtin_amdgcn_mfma_f32_16x16x32_bf16(af[m], bf[n], acc[m][n], 0, 0, 0);
;           }
.LBB0_1535:
	s_or_b64 exec, exec, s[6:7]
	s_waitcnt vmcnt(5)
	s_barrier
	v_readfirstlane_b32 s6, v56
	s_add_i32 m0, s6, 0x10000
	v_lshl_add_u64 v[4:5], v[46:47], 0, s[42:43]
	global_load_lds_dwordx4 v[4:5], off
	v_or_b32_e32 v2, 0x1c0, v38
	s_add_i32 m0, s6, 0x18000
	v_lshl_add_u64 v[4:5], v[2:3], 1, s[18:19]
	global_load_lds_dwordx4 v[4:5], off
	s_add_i32 m0, s6, 0x12000
	v_lshl_add_u64 v[4:5], v[48:49], 0, s[42:43]
	global_load_lds_dwordx4 v[4:5], off
	s_add_i32 m0, s6, 0x14000
	v_lshl_add_u64 v[4:5], v[50:51], 0, s[42:43]
	global_load_lds_dwordx4 v[4:5], off
	s_add_i32 m0, s6, 0x16000
	v_lshl_add_u64 v[4:5], v[52:53], 0, s[42:43]
	global_load_lds_dwordx4 v[4:5], off
	s_and_saveexec_b64 s[6:7], s[4:5]
	s_cbranch_execz .LBB0_1537
	ds_read_b128 v[94:97], v119 offset:32768
	ds_read_b128 v[98:101], v119 offset:34816
	ds_read_b128 v[102:105], v118
	ds_read_b128 v[106:109], v118 offset:2048
	s_waitcnt lgkmcnt(0)
	v_mfma_f32_16x16x32_bf16 v[34:37], v[94:97], v[102:105], v[34:37]
	v_mfma_f32_16x16x32_bf16 v[30:33], v[98:101], v[102:105], v[30:33]
	v_mfma_f32_16x16x32_bf16 v[26:29], v[94:97], v[106:109], v[26:29]
	v_mfma_f32_16x16x32_bf16 v[22:25], v[98:101], v[106:109], v[22:25]
	ds_read_b128 v[102:105], v118 offset:4096
	ds_read_b128 v[106:109], v118 offset:6144
	s_waitcnt lgkmcnt(0)
	v_mfma_f32_16x16x32_bf16 v[18:21], v[94:97], v[102:105], v[18:21]
	v_mfma_f32_16x16x32_bf16 v[10:13], v[94:97], v[106:109], v[10:13]
	ds_read_b128 v[94:97], v121 offset:32768
	v_mfma_f32_16x16x32_bf16 v[14:17], v[98:101], v[102:105], v[14:17]
	v_mfma_f32_16x16x32_bf16 v[4:7], v[98:101], v[106:109], v[6:9]
	ds_read_b128 v[98:101], v121 offset:34816
	ds_read_b128 v[102:105], v120
	ds_read_b128 v[106:109], v120 offset:2048
	s_waitcnt lgkmcnt(0)
	v_mfma_f32_16x16x32_bf16 v[34:37], v[94:97], v[102:105], v[34:37]
	v_mfma_f32_16x16x32_bf16 v[30:33], v[98:101], v[102:105], v[30:33]
	v_mfma_f32_16x16x32_bf16 v[26:29], v[94:97], v[106:109], v[26:29]
	v_mfma_f32_16x16x32_bf16 v[22:25], v[98:101], v[106:109], v[22:25]
	ds_read_b128 v[102:105], v120 offset:4096
	ds_read_b128 v[106:109], v120 offset:6144
	s_waitcnt lgkmcnt(0)
	v_mfma_f32_16x16x32_bf16 v[18:21], v[94:97], v[102:105], v[18:21]
	v_mfma_f32_16x16x32_bf16 v[14:17], v[98:101], v[102:105], v[14:17]
	v_mfma_f32_16x16x32_bf16 v[10:13], v[94:97], v[106:109], v[10:13]
	v_mfma_f32_16x16x32_bf16 v[6:9], v[98:101], v[106:109], v[4:7]
.LBB0_1537:
	s_or_b64 exec, exec, s[6:7]
	s_waitcnt vmcnt(5)
	s_barrier
	v_readfirstlane_b32 s6, v56
	s_add_i32 m0, s6, 0x1a000
	v_lshl_add_u64 v[4:5], v[46:47], 0, s[44:45]
	global_load_lds_dwordx4 v[4:5], off
	v_or_b32_e32 v2, 0x200, v38
	s_add_i32 m0, s6, 0x22000
	v_lshl_add_u64 v[4:5], v[2:3], 1, s[18:19]
	global_load_lds_dwordx4 v[4:5], off
	s_add_i32 m0, s6, 0x1c000
	v_lshl_add_u64 v[4:5], v[48:49], 0, s[44:45]
	global_load_lds_dwordx4 v[4:5], off
	s_add_i32 m0, s6, 0x1e000
	v_lshl_add_u64 v[4:5], v[50:51], 0, s[44:45]
	global_load_lds_dwordx4 v[4:5], off
	s_add_i32 m0, s6, 0x20000
	v_lshl_add_u64 v[4:5], v[52:53], 0, s[44:45]
	global_load_lds_dwordx4 v[4:5], off
	s_and_saveexec_b64 s[6:7], s[4:5]
	s_cbranch_execz .LBB0_1539
	ds_read_b128 v[94:97], v83 offset:32768
	ds_read_b128 v[98:101], v83 offset:34816
	ds_read_b128 v[102:105], v82
	ds_read_b128 v[106:109], v82 offset:2048
	s_waitcnt lgkmcnt(0)
	v_mfma_f32_16x16x32_bf16 v[34:37], v[94:97], v[102:105], v[34:37]
	v_mfma_f32_16x16x32_bf16 v[30:33], v[98:101], v[102:105], v[30:33]
	v_mfma_f32_16x16x32_bf16 v[26:29], v[94:97], v[106:109], v[26:29]
	v_mfma_f32_16x16x32_bf16 v[22:25], v[98:101], v[106:109], v[22:25]
	ds_read_b128 v[102:105], v82 offset:4096
	ds_read_b128 v[106:109], v82 offset:6144
	s_waitcnt lgkmcnt(0)
	v_mfma_f32_16x16x32_bf16 v[18:21], v[94:97], v[102:105], v[18:21]
	v_mfma_f32_16x16x32_bf16 v[10:13], v[94:97], v[106:109], v[10:13]
	ds_read_b128 v[94:97], v85 offset:32768
	v_mfma_f32_16x16x32_bf16 v[14:17], v[98:101], v[102:105], v[14:17]
	v_mfma_f32_16x16x32_bf16 v[4:7], v[98:101], v[106:109], v[6:9]
	ds_read_b128 v[98:101], v85 offset:34816
	ds_read_b128 v[102:105], v84
	ds_read_b128 v[106:109], v84 offset:2048
	s_waitcnt lgkmcnt(0)
	v_mfma_f32_16x16x32_bf16 v[34:37], v[94:97], v[102:105], v[34:37]
	v_mfma_f32_16x16x32_bf16 v[30:33], v[98:101], v[102:105], v[30:33]
	v_mfma_f32_16x16x32_bf16 v[26:29], v[94:97], v[106:109], v[26:29]
	v_mfma_f32_16x16x32_bf16 v[22:25], v[98:101], v[106:109], v[22:25]
	ds_read_b128 v[102:105], v84 offset:4096
	ds_read_b128 v[106:109], v84 offset:6144
	s_waitcnt lgkmcnt(0)
	v_mfma_f32_16x16x32_bf16 v[18:21], v[94:97], v[102:105], v[18:21]
	v_mfma_f32_16x16x32_bf16 v[14:17], v[98:101], v[102:105], v[14:17]
	v_mfma_f32_16x16x32_bf16 v[10:13], v[94:97], v[106:109], v[10:13]
	v_mfma_f32_16x16x32_bf16 v[6:9], v[98:101], v[106:109], v[4:7]
; #define GLDS16(gp, lp) __builtin_amdgcn_global_load_lds((const unsigned*)(gp), (__attribute__((address_space(3))) unsigned*)(lp), 16, 0, 0)
; template <bool SWAP, class Epi, bool THIN = false> ...
;     ...
;     for (int st = 0; st < ns; ++st) {
;       asm volatile("s_waitcnt vmcnt(0)" ::: "memory");
;       __builtin_amdgcn_s_barrier();
;       asm volatile("" ::: "memory");
;       if (st + 1 < ns) {
;         char* nb = smem + ((st + 1) & 1) * 65536;
;         const int ko = (st + 1) * 64;
; #pragma unroll
;         for (int i = 0; i < 4; ++i) { GLDS16(A + (size_t)(ap[i] + ko), nb + tid * 16 + i * 8192); GLDS16(Bt + (size_t)(bp[i] + ko), nb + 32768 + tid * 16 + i * 8192); }
;       }
;       const char* sa = smem + (st & 1) * 65536 + (wr * 64 + fr) * 128;
;       const char* sb = smem + (st & 1) * 65536 + 32768 + (wc * 128 + fr) * 128;
;       if constexpr (THIN) {
;         if (wc == 0) {
; #pragma unroll
;           for (int ks = 0; ks < 2; ++ks) {
;             bf16x8 af[4], bf[2];
; #pragma unroll
;             for (int m = 0; m < 4; ++m) af[m] = *(const bf16x8*)(sa + m * 2048 + (((ks * 4 + fq) ^ swz) << 4));
; #pragma unroll
;             for (int n = 0; n < 2; ++n) bf[n] = *(const bf16x8*)(sb + n * 2048 + (((ks * 4 + fq) ^ swz) << 4));
; #pragma unroll
;             for (int m = 0; m < 4; ++m)
; #pragma unroll
;               for (int n = 0; n < 2; ++n)
;                 acc[m][n] = SWAP ? __builtin_amdgcn_mfma_f32_16x16x32_bf16(bf[n], af[m], acc[m][n], 0, 0, 0)
;                                  : __builtin_amdgcn_mfma_f32_16x16x32_bf16(af[m], bf[n], acc[m][n], 0, 0, 0);
;           }
.LBB0_1539:
	s_or_b64 exec, exec, s[6:7]
	s_waitcnt vmcnt(5)
	s_barrier
	v_readfirstlane_b32 s6, v56
	s_add_i32 m0, s6, 0x0
	v_lshl_add_u64 v[4:5], v[46:47], 0, s[48:49]
	global_load_lds_dwordx4 v[4:5], off
	v_or_b32_e32 v2, 0x240, v38
	s_add_i32 m0, s6, 0x8000
	v_lshl_add_u64 v[4:5], v[2:3], 1, s[18:19]
	global_load_lds_dwordx4 v[4:5], off
	s_add_i32 m0, s6, 0x2000
	v_lshl_add_u64 v[4:5], v[48:49], 0, s[48:49]
	global_load_lds_dwordx4 v[4:5], off
	s_add_i32 m0, s6, 0x4000
	v_lshl_add_u64 v[4:5], v[50:51], 0, s[48:49]
	global_load_lds_dwordx4 v[4:5], off
	s_add_i32 m0, s6, 0x6000
	v_lshl_add_u64 v[4:5], v[52:53], 0, s[48:49]
	global_load_lds_dwordx4 v[4:5], off
	s_and_saveexec_b64 s[6:7], s[4:5]
	s_cbranch_execz .LBB0_1541
	ds_read_b128 v[94:97], v87
	ds_read_b128 v[98:101], v87 offset:2048
	ds_read_b128 v[102:105], v86
	ds_read_b128 v[106:109], v86 offset:2048
	s_waitcnt lgkmcnt(0)
	v_mfma_f32_16x16x32_bf16 v[34:37], v[94:97], v[102:105], v[34:37]
	v_mfma_f32_16x16x32_bf16 v[30:33], v[98:101], v[102:105], v[30:33]
	v_mfma_f32_16x16x32_bf16 v[26:29], v[94:97], v[106:109], v[26:29]
	v_mfma_f32_16x16x32_bf16 v[22:25], v[98:101], v[106:109], v[22:25]
	ds_read_b128 v[102:105], v86 offset:4096
	ds_read_b128 v[106:109], v86 offset:6144
	s_waitcnt lgkmcnt(0)
	v_mfma_f32_16x16x32_bf16 v[18:21], v[94:97], v[102:105], v[18:21]
	v_mfma_f32_16x16x32_bf16 v[10:13], v[94:97], v[106:109], v[10:13]
	ds_read_b128 v[94:97], v89
	v_mfma_f32_16x16x32_bf16 v[14:17], v[98:101], v[102:105], v[14:17]
	v_mfma_f32_16x16x32_bf16 v[4:7], v[98:101], v[106:109], v[6:9]
	ds_read_b128 v[98:101], v89 offset:2048
	ds_read_b128 v[102:105], v88
	ds_read_b128 v[106:109], v88 offset:2048
	s_waitcnt lgkmcnt(0)
	v_mfma_f32_16x16x32_bf16 v[34:37], v[94:97], v[102:105], v[34:37]
	v_mfma_f32_16x16x32_bf16 v[30:33], v[98:101], v[102:105], v[30:33]
	v_mfma_f32_16x16x32_bf16 v[26:29], v[94:97], v[106:109], v[26:29]
	v_mfma_f32_16x16x32_bf16 v[22:25], v[98:101], v[106:109], v[22:25]
	ds_read_b128 v[102:105], v88 offset:4096
	ds_read_b128 v[106:109], v88 offset:6144
	s_waitcnt lgkmcnt(0)
	v_mfma_f32_16x16x32_bf16 v[18:21], v[94:97], v[102:105], v[18:21]
	v_mfma_f32_16x16x32_bf16 v[14:17], v[98:101], v[102:105], v[14:17]
	v_mfma_f32_16x16x32_bf16 v[10:13], v[94:97], v[106:109], v[10:13]
	v_mfma_f32_16x16x32_bf16 v[6:9], v[98:101], v[106:109], v[4:7]
.LBB0_1541:
	s_or_b64 exec, exec, s[6:7]
	s_waitcnt vmcnt(5)
	s_barrier
	v_readfirstlane_b32 s6, v56
	s_add_i32 m0, s6, 0x10000
	v_lshl_add_u64 v[4:5], v[46:47], 0, s[50:51]
	global_load_lds_dwordx4 v[4:5], off
	v_or_b32_e32 v2, 0x280, v38
	s_add_i32 m0, s6, 0x18000
	v_lshl_add_u64 v[4:5], v[2:3], 1, s[18:19]
	global_load_lds_dwordx4 v[4:5], off
	s_add_i32 m0, s6, 0x12000
	v_lshl_add_u64 v[4:5], v[48:49], 0, s[50:51]
	global_load_lds_dwordx4 v[4:5], off
	s_add_i32 m0, s6, 0x14000
	v_lshl_add_u64 v[4:5], v[50:51], 0, s[50:51]
	global_load_lds_dwordx4 v[4:5], off
	s_add_i32 m0, s6, 0x16000
	v_lshl_add_u64 v[4:5], v[52:53], 0, s[50:51]
	global_load_lds_dwordx4 v[4:5], off
	s_and_saveexec_b64 s[6:7], s[4:5]
	s_cbranch_execz .LBB0_1543
	ds_read_b128 v[94:97], v119 offset:32768
	ds_read_b128 v[98:101], v119 offset:34816
	ds_read_b128 v[102:105], v118
	ds_read_b128 v[106:109], v118 offset:2048
	s_waitcnt lgkmcnt(0)
	v_mfma_f32_16x16x32_bf16 v[34:37], v[94:97], v[102:105], v[34:37]
	v_mfma_f32_16x16x32_bf16 v[30:33], v[98:101], v[102:105], v[30:33]
	v_mfma_f32_16x16x32_bf16 v[26:29], v[94:97], v[106:109], v[26:29]
	v_mfma_f32_16x16x32_bf16 v[22:25], v[98:101], v[106:109], v[22:25]
	ds_read_b128 v[102:105], v118 offset:4096
	ds_read_b128 v[106:109], v118 offset:6144
	s_waitcnt lgkmcnt(0)
	v_mfma_f32_16x16x32_bf16 v[18:21], v[94:97], v[102:105], v[18:21]
	v_mfma_f32_16x16x32_bf16 v[10:13], v[94:97], v[106:109], v[10:13]
	ds_read_b128 v[94:97], v121 offset:32768
	v_mfma_f32_16x16x32_bf16 v[14:17], v[98:101], v[102:105], v[14:17]
	v_mfma_f32_16x16x32_bf16 v[4:7], v[98:101], v[106:109], v[6:9]
	ds_read_b128 v[98:101], v121 offset:34816
	ds_read_b128 v[102:105], v120
	ds_read_b128 v[106:109], v120 offset:2048
	s_waitcnt lgkmcnt(0)
	v_mfma_f32_16x16x32_bf16 v[34:37], v[94:97], v[102:105], v[34:37]
	v_mfma_f32_16x16x32_bf16 v[30:33], v[98:101], v[102:105], v[30:33]
	v_mfma_f32_16x16x32_bf16 v[26:29], v[94:97], v[106:109], v[26:29]
	v_mfma_f32_16x16x32_bf16 v[22:25], v[98:101], v[106:109], v[22:25]
	ds_read_b128 v[102:105], v120 offset:4096
	ds_read_b128 v[106:109], v120 offset:6144
	s_waitcnt lgkmcnt(0)
	v_mfma_f32_16x16x32_bf16 v[18:21], v[94:97], v[102:105], v[18:21]
	v_mfma_f32_16x16x32_bf16 v[14:17], v[98:101], v[102:105], v[14:17]
	v_mfma_f32_16x16x32_bf16 v[10:13], v[94:97], v[106:109], v[10:13]
	v_mfma_f32_16x16x32_bf16 v[6:9], v[98:101], v[106:109], v[4:7]
; #define GLDS16(gp, lp) __builtin_amdgcn_global_load_lds((const unsigned*)(gp), (__attribute__((address_space(3))) unsigned*)(lp), 16, 0, 0)
; template <bool SWAP, class Epi, bool THIN = false> ...
;     ...
;     for (int st = 0; st < ns; ++st) {
;       asm volatile("s_waitcnt vmcnt(0)" ::: "memory");
;       __builtin_amdgcn_s_barrier();
;       asm volatile("" ::: "memory");
;       if (st + 1 < ns) {
;         char* nb = smem + ((st + 1) & 1) * 65536;
;         const int ko = (st + 1) * 64;
; #pragma unroll
;         for (int i = 0; i < 4; ++i) { GLDS16(A + (size_t)(ap[i] + ko), nb + tid * 16 + i * 8192); GLDS16(Bt + (size_t)(bp[i] + ko), nb + 32768 + tid * 16 + i * 8192); }
;       }
;       const char* sa = smem + (st & 1) * 65536 + (wr * 64 + fr) * 128;
;       const char* sb = smem + (st & 1) * 65536 + 32768 + (wc * 128 + fr) * 128;
;       if constexpr (THIN) {
;         if (wc == 0) {
; #pragma unroll
;           for (int ks = 0; ks < 2; ++ks) {
;             bf16x8 af[4], bf[2];
; #pragma unroll
;             for (int m = 0; m < 4; ++m) af[m] = *(const bf16x8*)(sa + m * 2048 + (((ks * 4 + fq) ^ swz) << 4));
; #pragma unroll
;             for (int n = 0; n < 2; ++n) bf[n] = *(const bf16x8*)(sb + n * 2048 + (((ks * 4 + fq) ^ swz) << 4));
; #pragma unroll
;             for (int m = 0; m < 4; ++m)
; #pragma unroll
;               for (int n = 0; n < 2; ++n)
;                 acc[m][n] = SWAP ? __builtin_amdgcn_mfma_f32_16x16x32_bf16(bf[n], af[m], acc[m][n], 0, 0, 0)
;                                  : __builtin_amdgcn_mfma_f32_16x16x32_bf16(af[m], bf[n], acc[m][n], 0, 0, 0);
;           }
.LBB0_1543:
	s_or_b64 exec, exec, s[6:7]
	s_waitcnt vmcnt(5)
	s_barrier
	v_readfirstlane_b32 s6, v56
	s_add_i32 m0, s6, 0x1a000
	v_lshl_add_u64 v[4:5], v[46:47], 0, s[56:57]
	global_load_lds_dwordx4 v[4:5], off
	v_or_b32_e32 v2, 0x2c0, v38
	s_add_i32 m0, s6, 0x22000
	v_lshl_add_u64 v[4:5], v[2:3], 1, s[18:19]
	global_load_lds_dwordx4 v[4:5], off
	s_add_i32 m0, s6, 0x1c000
	v_lshl_add_u64 v[4:5], v[48:49], 0, s[56:57]
	global_load_lds_dwordx4 v[4:5], off
	s_add_i32 m0, s6, 0x1e000
	v_lshl_add_u64 v[4:5], v[50:51], 0, s[56:57]
	global_load_lds_dwordx4 v[4:5], off
	s_add_i32 m0, s6, 0x20000
	v_lshl_add_u64 v[4:5], v[52:53], 0, s[56:57]
	global_load_lds_dwordx4 v[4:5], off
	s_and_saveexec_b64 s[6:7], s[4:5]
	s_cbranch_execz .LBB0_1545
	ds_read_b128 v[94:97], v83 offset:32768
	ds_read_b128 v[98:101], v83 offset:34816
	ds_read_b128 v[102:105], v82
	ds_read_b128 v[106:109], v82 offset:2048
	s_waitcnt lgkmcnt(0)
	v_mfma_f32_16x16x32_bf16 v[34:37], v[94:97], v[102:105], v[34:37]
	v_mfma_f32_16x16x32_bf16 v[30:33], v[98:101], v[102:105], v[30:33]
	v_mfma_f32_16x16x32_bf16 v[26:29], v[94:97], v[106:109], v[26:29]
	v_mfma_f32_16x16x32_bf16 v[22:25], v[98:101], v[106:109], v[22:25]
	ds_read_b128 v[102:105], v82 offset:4096
	ds_read_b128 v[106:109], v82 offset:6144
	s_waitcnt lgkmcnt(0)
	v_mfma_f32_16x16x32_bf16 v[18:21], v[94:97], v[102:105], v[18:21]
	v_mfma_f32_16x16x32_bf16 v[10:13], v[94:97], v[106:109], v[10:13]
	ds_read_b128 v[94:97], v85 offset:32768
	v_mfma_f32_16x16x32_bf16 v[14:17], v[98:101], v[102:105], v[14:17]
	v_mfma_f32_16x16x32_bf16 v[4:7], v[98:101], v[106:109], v[6:9]
	ds_read_b128 v[98:101], v85 offset:34816
	ds_read_b128 v[102:105], v84
	ds_read_b128 v[106:109], v84 offset:2048
	s_waitcnt lgkmcnt(0)
	v_mfma_f32_16x16x32_bf16 v[34:37], v[94:97], v[102:105], v[34:37]
	v_mfma_f32_16x16x32_bf16 v[30:33], v[98:101], v[102:105], v[30:33]
	v_mfma_f32_16x16x32_bf16 v[26:29], v[94:97], v[106:109], v[26:29]
	v_mfma_f32_16x16x32_bf16 v[22:25], v[98:101], v[106:109], v[22:25]
	ds_read_b128 v[102:105], v84 offset:4096
	ds_read_b128 v[106:109], v84 offset:6144
	s_waitcnt lgkmcnt(0)
	v_mfma_f32_16x16x32_bf16 v[18:21], v[94:97], v[102:105], v[18:21]
	v_mfma_f32_16x16x32_bf16 v[14:17], v[98:101], v[102:105], v[14:17]
	v_mfma_f32_16x16x32_bf16 v[10:13], v[94:97], v[106:109], v[10:13]
	v_mfma_f32_16x16x32_bf16 v[6:9], v[98:101], v[106:109], v[4:7]
.LBB0_1545:
	s_or_b64 exec, exec, s[6:7]
	s_waitcnt vmcnt(5)
	s_barrier
	v_readfirstlane_b32 s6, v56
	s_add_i32 m0, s6, 0x0
	v_lshl_add_u64 v[4:5], v[46:47], 0, s[58:59]
	global_load_lds_dwordx4 v[4:5], off
	v_or_b32_e32 v2, 0x300, v38
	s_add_i32 m0, s6, 0x8000
	v_lshl_add_u64 v[4:5], v[2:3], 1, s[18:19]
	global_load_lds_dwordx4 v[4:5], off
	s_add_i32 m0, s6, 0x2000
	v_lshl_add_u64 v[4:5], v[48:49], 0, s[58:59]
	global_load_lds_dwordx4 v[4:5], off
	s_add_i32 m0, s6, 0x4000
	v_lshl_add_u64 v[4:5], v[50:51], 0, s[58:59]
	global_load_lds_dwordx4 v[4:5], off
	s_add_i32 m0, s6, 0x6000
	v_lshl_add_u64 v[4:5], v[52:53], 0, s[58:59]
	global_load_lds_dwordx4 v[4:5], off
	s_and_saveexec_b64 s[6:7], s[4:5]
	s_cbranch_execz .LBB0_1547
	ds_read_b128 v[94:97], v87
	ds_read_b128 v[98:101], v87 offset:2048
	ds_read_b128 v[102:105], v86
	ds_read_b128 v[106:109], v86 offset:2048
	s_waitcnt lgkmcnt(0)
	v_mfma_f32_16x16x32_bf16 v[34:37], v[94:97], v[102:105], v[34:37]
	v_mfma_f32_16x16x32_bf16 v[30:33], v[98:101], v[102:105], v[30:33]
	v_mfma_f32_16x16x32_bf16 v[26:29], v[94:97], v[106:109], v[26:29]
	v_mfma_f32_16x16x32_bf16 v[22:25], v[98:101], v[106:109], v[22:25]
	ds_read_b128 v[102:105], v86 offset:4096
	ds_read_b128 v[106:109], v86 offset:6144
	s_waitcnt lgkmcnt(0)
	v_mfma_f32_16x16x32_bf16 v[18:21], v[94:97], v[102:105], v[18:21]
	v_mfma_f32_16x16x32_bf16 v[10:13], v[94:97], v[106:109], v[10:13]
	ds_read_b128 v[94:97], v89
	v_mfma_f32_16x16x32_bf16 v[14:17], v[98:101], v[102:105], v[14:17]
	v_mfma_f32_16x16x32_bf16 v[4:7], v[98:101], v[106:109], v[6:9]
	ds_read_b128 v[98:101], v89 offset:2048
	ds_read_b128 v[102:105], v88
	ds_read_b128 v[106:109], v88 offset:2048
	s_waitcnt lgkmcnt(0)
	v_mfma_f32_16x16x32_bf16 v[34:37], v[94:97], v[102:105], v[34:37]
	v_mfma_f32_16x16x32_bf16 v[30:33], v[98:101], v[102:105], v[30:33]
	v_mfma_f32_16x16x32_bf16 v[26:29], v[94:97], v[106:109], v[26:29]
	v_mfma_f32_16x16x32_bf16 v[22:25], v[98:101], v[106:109], v[22:25]
	ds_read_b128 v[102:105], v88 offset:4096
	ds_read_b128 v[106:109], v88 offset:6144
	s_waitcnt lgkmcnt(0)
	v_mfma_f32_16x16x32_bf16 v[18:21], v[94:97], v[102:105], v[18:21]
	v_mfma_f32_16x16x32_bf16 v[14:17], v[98:101], v[102:105], v[14:17]
	v_mfma_f32_16x16x32_bf16 v[10:13], v[94:97], v[106:109], v[10:13]
	v_mfma_f32_16x16x32_bf16 v[6:9], v[98:101], v[106:109], v[4:7]
; #define GLDS16(gp, lp) __builtin_amdgcn_global_load_lds((const unsigned*)(gp), (__attribute__((address_space(3))) unsigned*)(lp), 16, 0, 0)
; template <bool SWAP, class Epi, bool THIN = false> ...
;     ...
;     for (int st = 0; st < ns; ++st) {
;       asm volatile("s_waitcnt vmcnt(0)" ::: "memory");
;       __builtin_amdgcn_s_barrier();
;       asm volatile("" ::: "memory");
;       if (st + 1 < ns) {
;         char* nb = smem + ((st + 1) & 1) * 65536;
;         const int ko = (st + 1) * 64;
; #pragma unroll
;         for (int i = 0; i < 4; ++i) { GLDS16(A + (size_t)(ap[i] + ko), nb + tid * 16 + i * 8192); GLDS16(Bt + (size_t)(bp[i] + ko), nb + 32768 + tid * 16 + i * 8192); }
;       }
;       const char* sa = smem + (st & 1) * 65536 + (wr * 64 + fr) * 128;
;       const char* sb = smem + (st & 1) * 65536 + 32768 + (wc * 128 + fr) * 128;
;       if constexpr (THIN) {
;         if (wc == 0) {
; #pragma unroll
;           for (int ks = 0; ks < 2; ++ks) {
;             bf16x8 af[4], bf[2];
; #pragma unroll
;             for (int m = 0; m < 4; ++m) af[m] = *(const bf16x8*)(sa + m * 2048 + (((ks * 4 + fq) ^ swz) << 4));
; #pragma unroll
;             for (int n = 0; n < 2; ++n) bf[n] = *(const bf16x8*)(sb + n * 2048 + (((ks * 4 + fq) ^ swz) << 4));
; #pragma unroll
;             for (int m = 0; m < 4; ++m)
; #pragma unroll
;               for (int n = 0; n < 2; ++n)
;                 acc[m][n] = SWAP ? __builtin_amdgcn_mfma_f32_16x16x32_bf16(bf[n], af[m], acc[m][n], 0, 0, 0)
;                                  : __builtin_amdgcn_mfma_f32_16x16x32_bf16(af[m], bf[n], acc[m][n], 0, 0, 0);
;           }
;         }
.LBB0_1547:
	s_or_b64 exec, exec, s[6:7]
	s_waitcnt vmcnt(5)
	s_barrier
	v_readfirstlane_b32 s6, v56
	s_add_i32 m0, s6, 0x10000
	v_lshl_add_u64 v[4:5], v[46:47], 0, s[60:61]
	global_load_lds_dwordx4 v[4:5], off
	v_or_b32_e32 v2, 0x340, v38
	s_add_i32 m0, s6, 0x18000
	v_lshl_add_u64 v[4:5], v[2:3], 1, s[18:19]
	global_load_lds_dwordx4 v[4:5], off
	s_add_i32 m0, s6, 0x12000
	v_lshl_add_u64 v[4:5], v[48:49], 0, s[60:61]
	global_load_lds_dwordx4 v[4:5], off
	s_add_i32 m0, s6, 0x14000
	v_lshl_add_u64 v[4:5], v[50:51], 0, s[60:61]
	global_load_lds_dwordx4 v[4:5], off
	s_add_i32 m0, s6, 0x16000
	v_lshl_add_u64 v[4:5], v[52:53], 0, s[60:61]
	global_load_lds_dwordx4 v[4:5], off
	s_and_saveexec_b64 s[6:7], s[4:5]
	s_cbranch_execz .LBB0_1549
	ds_read_b128 v[94:97], v119 offset:32768
	ds_read_b128 v[98:101], v119 offset:34816
	ds_read_b128 v[102:105], v118
	ds_read_b128 v[106:109], v118 offset:2048
	s_waitcnt lgkmcnt(0)
	v_mfma_f32_16x16x32_bf16 v[34:37], v[94:97], v[102:105], v[34:37]
	v_mfma_f32_16x16x32_bf16 v[30:33], v[98:101], v[102:105], v[30:33]
	v_mfma_f32_16x16x32_bf16 v[26:29], v[94:97], v[106:109], v[26:29]
	v_mfma_f32_16x16x32_bf16 v[22:25], v[98:101], v[106:109], v[22:25]
	ds_read_b128 v[102:105], v118 offset:4096
	ds_read_b128 v[106:109], v118 offset:6144
	s_waitcnt lgkmcnt(0)
	v_mfma_f32_16x16x32_bf16 v[18:21], v[94:97], v[102:105], v[18:21]
	v_mfma_f32_16x16x32_bf16 v[10:13], v[94:97], v[106:109], v[10:13]
	ds_read_b128 v[94:97], v121 offset:32768
	v_mfma_f32_16x16x32_bf16 v[14:17], v[98:101], v[102:105], v[14:17]
	v_mfma_f32_16x16x32_bf16 v[4:7], v[98:101], v[106:109], v[6:9]
	ds_read_b128 v[98:101], v121 offset:34816
	ds_read_b128 v[102:105], v120
	ds_read_b128 v[106:109], v120 offset:2048
	s_waitcnt lgkmcnt(0)
	v_mfma_f32_16x16x32_bf16 v[34:37], v[94:97], v[102:105], v[34:37]
	v_mfma_f32_16x16x32_bf16 v[30:33], v[98:101], v[102:105], v[30:33]
	v_mfma_f32_16x16x32_bf16 v[26:29], v[94:97], v[106:109], v[26:29]
	v_mfma_f32_16x16x32_bf16 v[22:25], v[98:101], v[106:109], v[22:25]
	ds_read_b128 v[102:105], v120 offset:4096
	ds_read_b128 v[106:109], v120 offset:6144
	s_waitcnt lgkmcnt(0)
	v_mfma_f32_16x16x32_bf16 v[18:21], v[94:97], v[102:105], v[18:21]
	v_mfma_f32_16x16x32_bf16 v[14:17], v[98:101], v[102:105], v[14:17]
	v_mfma_f32_16x16x32_bf16 v[10:13], v[94:97], v[106:109], v[10:13]
	v_mfma_f32_16x16x32_bf16 v[6:9], v[98:101], v[106:109], v[4:7]
.LBB0_1549:
	s_or_b64 exec, exec, s[6:7]
	s_waitcnt vmcnt(5)
	s_barrier
	v_readfirstlane_b32 s6, v56
	s_add_i32 m0, s6, 0x1a000
	v_lshl_add_u64 v[4:5], v[46:47], 0, s[62:63]
	global_load_lds_dwordx4 v[4:5], off
	v_or_b32_e32 v2, 0x380, v38
	s_add_i32 m0, s6, 0x22000
	v_lshl_add_u64 v[4:5], v[2:3], 1, s[18:19]
	global_load_lds_dwordx4 v[4:5], off
	s_add_i32 m0, s6, 0x1c000
	v_lshl_add_u64 v[4:5], v[48:49], 0, s[62:63]
	global_load_lds_dwordx4 v[4:5], off
	s_add_i32 m0, s6, 0x1e000
	v_lshl_add_u64 v[4:5], v[50:51], 0, s[62:63]
	global_load_lds_dwordx4 v[4:5], off
	s_add_i32 m0, s6, 0x20000
	v_lshl_add_u64 v[4:5], v[52:53], 0, s[62:63]
	global_load_lds_dwordx4 v[4:5], off
	s_and_saveexec_b64 s[6:7], s[4:5]
	s_cbranch_execz .LBB0_1551
	ds_read_b128 v[94:97], v83 offset:32768
	ds_read_b128 v[98:101], v83 offset:34816
	ds_read_b128 v[102:105], v82
	ds_read_b128 v[106:109], v82 offset:2048
	s_waitcnt lgkmcnt(0)
	v_mfma_f32_16x16x32_bf16 v[34:37], v[94:97], v[102:105], v[34:37]
	v_mfma_f32_16x16x32_bf16 v[30:33], v[98:101], v[102:105], v[30:33]
	v_mfma_f32_16x16x32_bf16 v[26:29], v[94:97], v[106:109], v[26:29]
	v_mfma_f32_16x16x32_bf16 v[22:25], v[98:101], v[106:109], v[22:25]
	ds_read_b128 v[102:105], v82 offset:4096
	ds_read_b128 v[106:109], v82 offset:6144
	s_waitcnt lgkmcnt(0)
	v_mfma_f32_16x16x32_bf16 v[18:21], v[94:97], v[102:105], v[18:21]
	v_mfma_f32_16x16x32_bf16 v[10:13], v[94:97], v[106:109], v[10:13]
	ds_read_b128 v[94:97], v85 offset:32768
	v_mfma_f32_16x16x32_bf16 v[14:17], v[98:101], v[102:105], v[14:17]
	v_mfma_f32_16x16x32_bf16 v[4:7], v[98:101], v[106:109], v[6:9]
	ds_read_b128 v[98:101], v85 offset:34816
	ds_read_b128 v[102:105], v84
	ds_read_b128 v[106:109], v84 offset:2048
	s_waitcnt lgkmcnt(0)
	v_mfma_f32_16x16x32_bf16 v[34:37], v[94:97], v[102:105], v[34:37]
	v_mfma_f32_16x16x32_bf16 v[30:33], v[98:101], v[102:105], v[30:33]
	v_mfma_f32_16x16x32_bf16 v[26:29], v[94:97], v[106:109], v[26:29]
	v_mfma_f32_16x16x32_bf16 v[22:25], v[98:101], v[106:109], v[22:25]
	ds_read_b128 v[102:105], v84 offset:4096
	ds_read_b128 v[106:109], v84 offset:6144
	s_waitcnt lgkmcnt(0)
	v_mfma_f32_16x16x32_bf16 v[18:21], v[94:97], v[102:105], v[18:21]
	v_mfma_f32_16x16x32_bf16 v[14:17], v[98:101], v[102:105], v[14:17]
	v_mfma_f32_16x16x32_bf16 v[10:13], v[94:97], v[106:109], v[10:13]
	v_mfma_f32_16x16x32_bf16 v[6:9], v[98:101], v[106:109], v[4:7]
; #define GLDS16(gp, lp) __builtin_amdgcn_global_load_lds((const unsigned*)(gp), (__attribute__((address_space(3))) unsigned*)(lp), 16, 0, 0)
; template <bool SWAP, class Epi, bool THIN = false> ...
;     ...
;     for (int st = 0; st < ns; ++st) {
;       asm volatile("s_waitcnt vmcnt(0)" ::: "memory");
;       __builtin_amdgcn_s_barrier();
;       asm volatile("" ::: "memory");
;       if (st + 1 < ns) {
;         char* nb = smem + ((st + 1) & 1) * 65536;
;         const int ko = (st + 1) * 64;
; #pragma unroll
;         for (int i = 0; i < 4; ++i) { GLDS16(A + (size_t)(ap[i] + ko), nb + tid * 16 + i * 8192); GLDS16(Bt + (size_t)(bp[i] + ko), nb + 32768 + tid * 16 + i * 8192); }
;       }
;       const char* sa = smem + (st & 1) * 65536 + (wr * 64 + fr) * 128;
;       const char* sb = smem + (st & 1) * 65536 + 32768 + (wc * 128 + fr) * 128;
;       if constexpr (THIN) {
;         if (wc == 0) {
; #pragma unroll
;           for (int ks = 0; ks < 2; ++ks) {
;             bf16x8 af[4], bf[2];
; #pragma unroll
;             for (int m = 0; m < 4; ++m) af[m] = *(const bf16x8*)(sa + m * 2048 + (((ks * 4 + fq) ^ swz) << 4));
; #pragma unroll
;             for (int n = 0; n < 2; ++n) bf[n] = *(const bf16x8*)(sb + n * 2048 + (((ks * 4 + fq) ^ swz) << 4));
; #pragma unroll
;             for (int m = 0; m < 4; ++m)
; #pragma unroll
;               for (int n = 0; n < 2; ++n)
;                 acc[m][n] = SWAP ? __builtin_amdgcn_mfma_f32_16x16x32_bf16(bf[n], af[m], acc[m][n], 0, 0, 0)
;                                  : __builtin_amdgcn_mfma_f32_16x16x32_bf16(af[m], bf[n], acc[m][n], 0, 0, 0);
;           }
;         }
.LBB0_1551:
	s_or_b64 exec, exec, s[6:7]
	s_waitcnt vmcnt(5)
	s_barrier
	v_readfirstlane_b32 s6, v56
	s_add_i32 m0, s6, 0x0
	v_lshl_add_u64 v[4:5], v[46:47], 0, s[64:65]
	global_load_lds_dwordx4 v[4:5], off
	v_or_b32_e32 v2, 0x3c0, v38
	s_add_i32 m0, s6, 0x8000
	v_lshl_add_u64 v[4:5], v[2:3], 1, s[18:19]
	global_load_lds_dwordx4 v[4:5], off
	s_add_i32 m0, s6, 0x2000
	v_lshl_add_u64 v[4:5], v[48:49], 0, s[64:65]
	global_load_lds_dwordx4 v[4:5], off
	s_add_i32 m0, s6, 0x4000
	v_lshl_add_u64 v[4:5], v[50:51], 0, s[64:65]
	global_load_lds_dwordx4 v[4:5], off
	s_add_i32 m0, s6, 0x6000
	v_lshl_add_u64 v[4:5], v[52:53], 0, s[64:65]
	global_load_lds_dwordx4 v[4:5], off
	s_and_saveexec_b64 s[6:7], s[4:5]
	s_cbranch_execz .LBB0_1553
	ds_read_b128 v[94:97], v87
	ds_read_b128 v[98:101], v87 offset:2048
	ds_read_b128 v[102:105], v86
	ds_read_b128 v[106:109], v86 offset:2048
	s_waitcnt lgkmcnt(0)
	v_mfma_f32_16x16x32_bf16 v[34:37], v[94:97], v[102:105], v[34:37]
	v_mfma_f32_16x16x32_bf16 v[30:33], v[98:101], v[102:105], v[30:33]
	v_mfma_f32_16x16x32_bf16 v[26:29], v[94:97], v[106:109], v[26:29]
	v_mfma_f32_16x16x32_bf16 v[22:25], v[98:101], v[106:109], v[22:25]
	ds_read_b128 v[102:105], v86 offset:4096
	ds_read_b128 v[106:109], v86 offset:6144
	s_waitcnt lgkmcnt(0)
	v_mfma_f32_16x16x32_bf16 v[18:21], v[94:97], v[102:105], v[18:21]
	v_mfma_f32_16x16x32_bf16 v[10:13], v[94:97], v[106:109], v[10:13]
	ds_read_b128 v[94:97], v89
	v_mfma_f32_16x16x32_bf16 v[14:17], v[98:101], v[102:105], v[14:17]
	v_mfma_f32_16x16x32_bf16 v[4:7], v[98:101], v[106:109], v[6:9]
	ds_read_b128 v[98:101], v89 offset:2048
	ds_read_b128 v[102:105], v88
	ds_read_b128 v[106:109], v88 offset:2048
	s_waitcnt lgkmcnt(0)
	v_mfma_f32_16x16x32_bf16 v[34:37], v[94:97], v[102:105], v[34:37]
	v_mfma_f32_16x16x32_bf16 v[30:33], v[98:101], v[102:105], v[30:33]
	v_mfma_f32_16x16x32_bf16 v[26:29], v[94:97], v[106:109], v[26:29]
	v_mfma_f32_16x16x32_bf16 v[22:25], v[98:101], v[106:109], v[22:25]
	ds_read_b128 v[102:105], v88 offset:4096
	ds_read_b128 v[106:109], v88 offset:6144
	s_waitcnt lgkmcnt(0)
	v_mfma_f32_16x16x32_bf16 v[18:21], v[94:97], v[102:105], v[18:21]
	v_mfma_f32_16x16x32_bf16 v[14:17], v[98:101], v[102:105], v[14:17]
	v_mfma_f32_16x16x32_bf16 v[10:13], v[94:97], v[106:109], v[10:13]
	v_mfma_f32_16x16x32_bf16 v[6:9], v[98:101], v[106:109], v[4:7]
.LBB0_1553:
	s_or_b64 exec, exec, s[6:7]
	s_waitcnt vmcnt(5)
	s_barrier
	s_and_saveexec_b64 s[6:7], s[4:5]
	s_cbranch_execz .LBB0_1555
	ds_read_b128 v[38:41], v119 offset:32768
	ds_read_b128 v[42:45], v119 offset:34816
	ds_read_b128 v[46:49], v118
	ds_read_b128 v[50:53], v118 offset:2048
	s_waitcnt lgkmcnt(0)
	v_mfma_f32_16x16x32_bf16 v[34:37], v[38:41], v[46:49], v[34:37]
	v_mfma_f32_16x16x32_bf16 v[30:33], v[42:45], v[46:49], v[30:33]
	v_mfma_f32_16x16x32_bf16 v[26:29], v[38:41], v[50:53], v[26:29]
	v_mfma_f32_16x16x32_bf16 v[22:25], v[42:45], v[50:53], v[22:25]
	ds_read_b128 v[46:49], v118 offset:4096
	ds_read_b128 v[50:53], v118 offset:6144
	s_waitcnt lgkmcnt(0)
	v_mfma_f32_16x16x32_bf16 v[18:21], v[38:41], v[46:49], v[18:21]
	v_mfma_f32_16x16x32_bf16 v[10:13], v[38:41], v[50:53], v[10:13]
	ds_read_b128 v[38:41], v121 offset:32768
	v_mfma_f32_16x16x32_bf16 v[14:17], v[42:45], v[46:49], v[14:17]
	v_mfma_f32_16x16x32_bf16 v[4:7], v[42:45], v[50:53], v[6:9]
	ds_read_b128 v[42:45], v121 offset:34816
	ds_read_b128 v[46:49], v120
	ds_read_b128 v[50:53], v120 offset:2048
	s_waitcnt lgkmcnt(0)
	v_mfma_f32_16x16x32_bf16 v[34:37], v[38:41], v[46:49], v[34:37]
	v_mfma_f32_16x16x32_bf16 v[30:33], v[42:45], v[46:49], v[30:33]
	v_mfma_f32_16x16x32_bf16 v[26:29], v[38:41], v[50:53], v[26:29]
	v_mfma_f32_16x16x32_bf16 v[22:25], v[42:45], v[50:53], v[22:25]
	ds_read_b128 v[46:49], v120 offset:4096
	ds_read_b128 v[50:53], v120 offset:6144
	s_waitcnt lgkmcnt(0)
	v_mfma_f32_16x16x32_bf16 v[18:21], v[38:41], v[46:49], v[18:21]
	v_mfma_f32_16x16x32_bf16 v[14:17], v[42:45], v[46:49], v[14:17]
	v_mfma_f32_16x16x32_bf16 v[10:13], v[38:41], v[50:53], v[10:13]
	v_mfma_f32_16x16x32_bf16 v[6:9], v[42:45], v[50:53], v[4:7]
.LBB0_1555:
	s_or_b64 exec, exec, s[6:7]
	s_waitcnt vmcnt(0)
	s_barrier
	s_and_saveexec_b64 s[6:7], s[4:5]
	s_xor_b64 s[6:7], exec, s[6:7]
	s_cbranch_execz .LBB0_1557
	ds_read_b128 v[38:41], v83 offset:32768
	ds_read_b128 v[42:45], v83 offset:34816
	ds_read_b128 v[46:49], v82
	ds_read_b128 v[50:53], v82 offset:2048
	s_waitcnt lgkmcnt(0)
	v_mfma_f32_16x16x32_bf16 v[34:37], v[38:41], v[46:49], v[34:37]
	v_mfma_f32_16x16x32_bf16 v[30:33], v[42:45], v[46:49], v[30:33]
	v_mfma_f32_16x16x32_bf16 v[26:29], v[38:41], v[50:53], v[26:29]
	v_mfma_f32_16x16x32_bf16 v[22:25], v[42:45], v[50:53], v[22:25]
	ds_read_b128 v[46:49], v82 offset:4096
	ds_read_b128 v[50:53], v82 offset:6144
	s_waitcnt lgkmcnt(0)
	v_mfma_f32_16x16x32_bf16 v[18:21], v[38:41], v[46:49], v[18:21]
	v_mfma_f32_16x16x32_bf16 v[10:13], v[38:41], v[50:53], v[10:13]
	ds_read_b128 v[38:41], v85 offset:32768
	v_mfma_f32_16x16x32_bf16 v[14:17], v[42:45], v[46:49], v[14:17]
	v_mfma_f32_16x16x32_bf16 v[4:7], v[42:45], v[50:53], v[6:9]
	ds_read_b128 v[42:45], v85 offset:34816
	ds_read_b128 v[46:49], v84
	ds_read_b128 v[50:53], v84 offset:2048
	s_waitcnt lgkmcnt(0)
	v_mfma_f32_16x16x32_bf16 v[34:37], v[38:41], v[46:49], v[34:37]
	v_mfma_f32_16x16x32_bf16 v[30:33], v[42:45], v[46:49], v[30:33]
	v_mfma_f32_16x16x32_bf16 v[26:29], v[38:41], v[50:53], v[26:29]
	v_mfma_f32_16x16x32_bf16 v[22:25], v[42:45], v[50:53], v[22:25]
	ds_read_b128 v[46:49], v84 offset:4096
	ds_read_b128 v[50:53], v84 offset:6144
	s_waitcnt lgkmcnt(0)
	v_mfma_f32_16x16x32_bf16 v[18:21], v[38:41], v[46:49], v[18:21]
	v_mfma_f32_16x16x32_bf16 v[14:17], v[42:45], v[46:49], v[14:17]
	v_mfma_f32_16x16x32_bf16 v[10:13], v[38:41], v[50:53], v[10:13]
	v_mfma_f32_16x16x32_bf16 v[6:9], v[42:45], v[50:53], v[4:7]
